# attn: K-tile 16-slot LDS swizzle (conflict-free ds_read_b128) + 3-deep K-fragment read pipeline in QK
# speedup vs baseline: 1.0040x; 1.0040x over previous
; #define LAS __attribute__((address_space(3)))
; __device__ __forceinline__ int v_rd_base(int lane) { return ((lane & 3) << 3) | (((lane >> 2) & 3) << 6) | (((lane >> 4) & 1) << 5) | (((lane >> 5) & 1) << 8); }
; __device__ __forceinline__ void body(const bf16_t* __restrict__ Qb, const bf16_t* __restrict__ Kh, const bf16_t* __restrict__ Vh, bf16_t* __restrict__ Ob, int seq, char* lds) {
;     ...
;   float m_reg = -1e30f, l_reg = 0; f32x16 o[8] = {}; bf16x8 qr[8];
;   const bf16_t* Qw = Qb + (long)(wid * QBLK + r32) * LDQ + hi * 8;
; #pragma unroll
;   for (int d0 = 0; d0 < 8; ++d0) qr[d0] = *reinterpret_cast<const bf16x8*>(Qw + d0 * 16);
;   const int wu = __builtin_amdgcn_readfirstlane(wid);
;   int koff[2], voff[4];
; #pragma unroll
;   for (int q = 0; q < 2; ++q) { const int row = 4 * (wu * 2 + q) + (lane >> 4); koff[q] = row * LDK + ((((lane & 15) << 4) ^ ((row & 7) << 4)) >> 1); }
; #pragma unroll
;   for (int q = 0; q < 4; ++q) { const int s = 2 * (wu * 4 + q) + (lane >> 5), kk = (s >> 3) * 8 + ((lane & 31) >> 2), k = (kk & ~0xC) | ((kk & 4) << 1) | ((kk & 8) >> 1);
;     voff[q] = k * LDV + (s & 7) * 32 + (lane & 3) * 8; }
;   const int vb0 = (int)(uintptr_t)(LAS char*)V_lds + v_rd_base(lane);
;   LAS char* Vl = (LAS char*)V_lds; LAS char* Kl = (LAS char*)K_lds;
;     ...
;   const int NT = seq / KVBLK;
;   if (wu >= 4) __builtin_amdgcn_s_setprio(2);
;   STAGE(0, 0);
;   asm volatile("s_waitcnt vmcnt(0) lgkmcnt(0)" ::: "memory"); __builtin_amdgcn_s_barrier(); asm volatile("" ::: "memory");
.LBB0_615:
	s_mul_i32 s9, s25, 0x44
	s_or_b32 s10, s9, s7
	s_ashr_i32 s11, s10, 31
	s_lshl_b64 s[12:13], s[10:11], 17
	s_add_u32 s7, s4, s12
	s_addc_u32 s9, s5, s13
	s_add_u32 s10, s7, s8
	s_addc_u32 s11, s9, 0
	v_and_b32_e32 v6, 63, v1
	s_add_u32 s12, s14, s12
	v_lshlrev_b32_e32 v3, 4, v1
	v_and_b32_e32 v5, 48, v1
	s_movk_i32 s8, 0xf0
	s_addc_u32 s13, s15, s13
	s_lshl_b32 s7, s6, 3
	v_lshrrev_b32_e32 v2, 4, v6
	v_and_b32_e32 v4, 0xf0, v3
	v_bitop3_b32 v3, v3, v5, s8 bitop3:0x6c
	v_or_b32_e32 v2, s7, v2
	v_lshrrev_b32_e32 v3, 1, v3
	v_lshl_or_b32 v214, v2, 8, v3
	v_or_b32_e32 v2, 4, v2
	v_lshlrev_b32_e32 v3, 4, v2
	s_movk_i32 s8, 0x70
	v_bitop3_b32 v3, v3, v4, s8 bitop3:0x6c
	v_lshrrev_b32_e32 v3, 1, v3
	v_lshl_or_b32 v216, v2, 8, v3
	v_lshrrev_b32_e32 v2, 2, v231
	v_bitop3_b32 v2, s7, v229, v2 bitop3:0xc8
	v_lshrrev_b32_e32 v3, 1, v231
	s_lshl_b32 s7, s6, 2
	v_and_b32_e32 v3, 8, v3
	s_and_b32 s7, s7, 4
	v_or3_b32 v2, v3, v2, s7
	s_lshl_b32 s7, s6, 11
	v_lshlrev_b32_e32 v4, 3, v1
	s_add_i32 s7, s7, 16
	v_lshlrev_b32_e32 v2, 8, v2
	v_and_b32_e32 v3, 32, v1
	v_and_b32_e32 v4, 24, v4
	s_add_i32 s27, s7, 0x10000
	v_lshrrev_b32_e32 v8, 4, v220
	v_and_b32_e32 v9, 3, v8
	v_lshrrev_b32_e32 v8, 2, v8
	v_lshl_or_b32 v8, v8, 3, v9
	v_and_b32_e32 v9, 15, v220
	v_xor_b32_e32 v10, v9, v8
	v_and_b32_e32 v10, 15, v10
	v_lshlrev_b32_e32 v10, 3, v10
	v_lshl_or_b32 v214, v8, 8, v10
	v_or_b32_e32 v8, 4, v8
	v_xor_b32_e32 v10, v9, v8
	v_and_b32_e32 v10, 15, v10
	v_lshlrev_b32_e32 v10, 3, v10
	v_lshl_or_b32 v216, v8, 8, v10
	v_ashrrev_i32_e32 v215, 31, v214
	v_or3_b32 v218, v2, v3, v4
	v_lshl_add_u64 v[2:3], v[214:215], 1, s[10:11]
	s_mov_b32 m0, s27
	v_ashrrev_i32_e32 v217, 31, v216
	s_lshl_b32 s6, s6, 12
	global_load_lds_dwordx4 v[2:3], off
	v_lshl_add_u64 v[2:3], v[216:217], 1, s[10:11]
	s_add_i32 m0, s7, 0x10400
	s_add_i32 s28, s6, 16
	v_ashrrev_i32_e32 v219, 31, v218
	global_load_lds_dwordx4 v[2:3], off
	v_lshl_add_u64 v[2:3], v[218:219], 1, s[12:13]
	s_mov_b32 m0, s28
	v_lshl_add_u64 v[4:5], v[2:3], 0, s[36:37]
	global_load_lds_dwordx4 v[2:3], off
	s_add_i32 m0, s28, 0x400
	v_and_b32_e32 v1, 0x3fffffc0, v1
	global_load_lds_dwordx4 v[4:5], off
	v_lshl_add_u64 v[4:5], v[2:3], 0, s[40:41]
	s_add_i32 m0, s28, 0x800
	v_lshl_add_u64 v[2:3], v[2:3], 0, s[46:47]
	global_load_lds_dwordx4 v[4:5], off
	s_add_i32 m0, s28, 0xc00
	s_add_i32 s6, 16, 0x18000
	global_load_lds_dwordx4 v[2:3], off
	v_lshlrev_b32_e32 v4, 4, v231
	v_lshl_add_u32 v211, v1, 2, s6
	v_and_b32_e32 v5, 0x70, v4
	s_movk_i32 s6, 0x60
	v_lshlrev_b32_e32 v3, 1, v6
	v_bitop3_b32 v236, v212, v5, s6 bitop3:0x36
	s_movk_i32 s6, 0xa0
	v_lshlrev_b32_e32 v1, 3, v6
	v_lshlrev_b32_e32 v2, 4, v6
	v_and_b32_e32 v3, 32, v3
	v_bitop3_b32 v233, v212, v4, s8 bitop3:0x78
	v_bitop3_b32 v239, v212, v5, s6 bitop3:0x36
	s_movk_i32 s6, 0xc0
	s_movk_i32 s8, 0x118
	v_and_b32_e32 v2, 0xc0, v2
	v_bitop3_b32 v240, v212, v5, s6 bitop3:0x36
	s_movk_i32 s6, 0xe0
	v_and_or_b32 v1, v1, s8, v3
	v_mov_b32_e32 v14, v0
	v_mov_b32_e32 v15, v0
	s_waitcnt vmcnt(0) lgkmcnt(0)
	s_barrier
	v_bitop3_b32 v234, v212, v5, 32 bitop3:0x36
	v_bitop3_b32 v235, v212, v5, 64 bitop3:0x36
	v_bitop3_b32 v238, v212, v5, s82 bitop3:0x36
	v_bitop3_b32 v241, v212, v5, s6 bitop3:0x36
	v_cmp_gt_u32_e64 s[6:7], 32, v6
	v_add3_u32 v242, v2, 16, v1
	v_mov_b32_e32 v1, v0
	v_mov_b32_e32 v2, v0
	v_mov_b32_e32 v3, v0
	v_mov_b32_e32 v4, v0
	v_mov_b32_e32 v5, v0
	v_mov_b32_e32 v6, v0
	v_mov_b32_e32 v7, v0
	v_mov_b32_e32 v8, v0
	v_mov_b32_e32 v9, v0
	v_mov_b32_e32 v10, v0
	v_mov_b32_e32 v11, v0
	v_mov_b32_e32 v12, v0
	v_mov_b32_e32 v13, v0
	v_mov_b64_e32 v[128:129], v[14:15]
	v_mov_b64_e32 v[112:113], v[14:15]
	v_mov_b64_e32 v[96:97], v[14:15]
	v_mov_b64_e32 v[80:81], v[14:15]
	v_mov_b64_e32 v[64:65], v[14:15]
	v_mov_b64_e32 v[48:49], v[14:15]
	v_mov_b64_e32 v[32:33], v[14:15]
	v_mov_b64_e32 v[126:127], v[12:13]
	v_mov_b64_e32 v[124:125], v[10:11]
	v_mov_b64_e32 v[122:123], v[8:9]
	v_mov_b64_e32 v[120:121], v[6:7]
	v_mov_b64_e32 v[118:119], v[4:5]
	v_mov_b64_e32 v[116:117], v[2:3]
	v_mov_b64_e32 v[114:115], v[0:1]
	v_mov_b64_e32 v[110:111], v[12:13]
	v_mov_b64_e32 v[108:109], v[10:11]
	v_mov_b64_e32 v[106:107], v[8:9]
	v_mov_b64_e32 v[104:105], v[6:7]
	v_mov_b64_e32 v[102:103], v[4:5]
	v_mov_b64_e32 v[100:101], v[2:3]
	v_mov_b64_e32 v[98:99], v[0:1]
	v_mov_b64_e32 v[94:95], v[12:13]
	v_mov_b64_e32 v[92:93], v[10:11]
	v_mov_b64_e32 v[90:91], v[8:9]
	v_mov_b64_e32 v[88:89], v[6:7]
	v_mov_b64_e32 v[86:87], v[4:5]
	v_mov_b64_e32 v[84:85], v[2:3]
	v_mov_b64_e32 v[82:83], v[0:1]
	v_mov_b64_e32 v[78:79], v[12:13]
	v_mov_b64_e32 v[76:77], v[10:11]
	v_mov_b64_e32 v[74:75], v[8:9]
	v_mov_b64_e32 v[72:73], v[6:7]
	v_mov_b64_e32 v[70:71], v[4:5]
	v_mov_b64_e32 v[68:69], v[2:3]
	v_mov_b64_e32 v[66:67], v[0:1]
	v_mov_b64_e32 v[62:63], v[12:13]
	v_mov_b64_e32 v[60:61], v[10:11]
	v_mov_b64_e32 v[58:59], v[8:9]
	v_mov_b64_e32 v[56:57], v[6:7]
	v_mov_b64_e32 v[54:55], v[4:5]
	v_mov_b64_e32 v[52:53], v[2:3]
	v_mov_b64_e32 v[50:51], v[0:1]
	v_mov_b64_e32 v[46:47], v[12:13]
	v_mov_b64_e32 v[44:45], v[10:11]
	v_mov_b64_e32 v[42:43], v[8:9]
	v_mov_b64_e32 v[40:41], v[6:7]
	v_mov_b64_e32 v[38:39], v[4:5]
	v_mov_b64_e32 v[36:37], v[2:3]
	v_mov_b64_e32 v[34:35], v[0:1]
	v_mov_b64_e32 v[30:31], v[12:13]
	v_mov_b64_e32 v[28:29], v[10:11]
	v_mov_b64_e32 v[26:27], v[8:9]
	v_mov_b64_e32 v[24:25], v[6:7]
	v_mov_b64_e32 v[22:23], v[4:5]
	v_mov_b64_e32 v[20:21], v[2:3]
	v_mov_b64_e32 v[18:19], v[0:1]
	v_mov_b64_e32 v[16:17], v[14:15]
	v_lshlrev_b32_e32 v213, 8, v231
	v_lshl_add_u32 v237, v231, 2, v211
	s_mov_b32 s29, 0
	v_mov_b32_e32 v244, 0
	v_mov_b32_e32 v243, 0xf149f2ca
	s_movk_i32 s33, 0x4000
	v_mov_b64_e32 v[14:15], v[12:13]
	v_mov_b64_e32 v[12:13], v[10:11]
	v_mov_b64_e32 v[10:11], v[8:9]
	v_mov_b64_e32 v[8:9], v[6:7]
	v_mov_b64_e32 v[6:7], v[4:5]
	v_mov_b64_e32 v[4:5], v[2:3]
	v_mov_b64_e32 v[2:3], v[0:1]
	v_lshlrev_b32_e32 v233, 4, v231
	v_and_b32_e32 v233, 0xf0, v233
	v_xor_b32_e32 v233, v233, v212
	v_xor_b32_e32 v234, 32, v233
	v_xor_b32_e32 v235, 64, v233
	v_xor_b32_e32 v236, 0x60, v233
	v_xor_b32_e32 v238, 0x80, v233
	v_xor_b32_e32 v239, 0xa0, v233
	v_xor_b32_e32 v240, 0xc0, v233
	v_xor_b32_e32 v241, 0xe0, v233
	s_waitcnt vmcnt(0)

; __device__ __forceinline__ void partialSM(f32x16& p0, f32x16& p1, float& m_reg, float& mn, float& alpha) {
;   constexpr float C = SCALE * 1.4426950408889634f;
;   float pmax = p0[0];
; #pragma unroll
;   for (int r = 1; r < 16; ++r) pmax = fmaxf(pmax, p0[r]);
; #pragma unroll
;   for (int r = 0; r < 16; ++r) pmax = fmaxf(pmax, p1[r]);
;   { auto rr = __builtin_amdgcn_permlane32_swap(__float_as_uint(pmax), __float_as_uint(pmax), false, false);
;     pmax = fmaxf(__uint_as_float(rr[0]), __uint_as_float(rr[1])); }
;   if (__builtin_expect(__all(pmax - m_reg <= THR / SCALE), 1)) { mn = m_reg; alpha = 1.f; }
;   else { mn = fmaxf(m_reg, pmax); alpha = __builtin_amdgcn_exp2f((m_reg - mn) * C); m_reg = mn; }
; __device__ __forceinline__ void qkt(f32x16& p0, f32x16& p1, const char* Ks, const bf16x8* qr, int r32, int hi) {
;   p0 = f32x16{}; p1 = f32x16{};
; #pragma unroll
;   for (int d0 = 0; d0 < 8; ++d0) { int cb = (d0 * 16 + hi * 8) * 2;
;     bf16x8 b0 = *reinterpret_cast<const bf16x8*>(Ks + KSWZ(r32, cb));
;     bf16x8 b1 = *reinterpret_cast<const bf16x8*>(Ks + KSWZ(32 + r32, cb));
;     p0 = __builtin_amdgcn_mfma_f32_32x32x16_bf16(b0, qr[d0], p0, 0, 0, 0);
;     p1 = __builtin_amdgcn_mfma_f32_32x32x16_bf16(b1, qr[d0], p1, 0, 0, 0); }
; }
.LBB0_620:
	s_add_i32 s8, s30, 0x10010
	v_add3_u32 v1, s8, v233, v213
	ds_read_b128 v[194:197], v1
	ds_read_b128 v[198:201], v1 offset:8192
	v_add3_u32 v1, s8, v234, v213
	ds_read_b128 v[202:205], v1
	ds_read_b128 v[206:209], v1 offset:8192
	v_add3_u32 v1, s8, v235, v213
	ds_read_b128 v[246:249], v1
	ds_read_b128 v[252:255], v1 offset:8192
	s_waitcnt lgkmcnt(4)
	v_mfma_f32_32x32x16_bf16 v[146:161], v[194:197], v[162:165], 0
	v_mfma_f32_32x32x16_bf16 v[130:145], v[198:201], v[162:165], 0
	v_add3_u32 v1, s8, v236, v213
	ds_read_b128 v[194:197], v1
	ds_read_b128 v[198:201], v1 offset:8192
	s_waitcnt lgkmcnt(4)
	v_mfma_f32_32x32x16_bf16 v[146:161], v[202:205], v[166:169], v[146:161]
	v_mfma_f32_32x32x16_bf16 v[130:145], v[206:209], v[166:169], v[130:145]
	v_add3_u32 v1, s8, v238, v213
	ds_read_b128 v[202:205], v1
	ds_read_b128 v[206:209], v1 offset:8192
	s_waitcnt lgkmcnt(4)
	v_mfma_f32_32x32x16_bf16 v[146:161], v[246:249], v[170:173], v[146:161]
	v_mfma_f32_32x32x16_bf16 v[130:145], v[252:255], v[170:173], v[130:145]
	v_add3_u32 v1, s8, v239, v213
	ds_read_b128 v[246:249], v1
	ds_read_b128 v[252:255], v1 offset:8192
	s_waitcnt lgkmcnt(4)
	v_mfma_f32_32x32x16_bf16 v[146:161], v[194:197], v[174:177], v[146:161]
	v_mfma_f32_32x32x16_bf16 v[130:145], v[198:201], v[174:177], v[130:145]
	v_add3_u32 v1, s8, v240, v213
	ds_read_b128 v[194:197], v1
	ds_read_b128 v[198:201], v1 offset:8192
	s_waitcnt lgkmcnt(4)
	v_mfma_f32_32x32x16_bf16 v[146:161], v[202:205], v[178:181], v[146:161]
	v_mfma_f32_32x32x16_bf16 v[130:145], v[206:209], v[178:181], v[130:145]
	v_add3_u32 v1, s8, v241, v213
	ds_read_b128 v[202:205], v1
	ds_read_b128 v[206:209], v1 offset:8192
	s_mov_b32 s8, 0x42b504f3
	s_waitcnt lgkmcnt(4)
	v_mfma_f32_32x32x16_bf16 v[146:161], v[246:249], v[182:185], v[146:161]
	v_mfma_f32_32x32x16_bf16 v[130:145], v[252:255], v[182:185], v[130:145]
	s_waitcnt lgkmcnt(2)
	v_mfma_f32_32x32x16_bf16 v[146:161], v[194:197], v[186:189], v[146:161]
	v_mfma_f32_32x32x16_bf16 v[130:145], v[198:201], v[186:189], v[130:145]
	s_waitcnt lgkmcnt(0)
	v_mfma_f32_32x32x16_bf16 v[146:161], v[202:205], v[190:193], v[146:161]
	v_mfma_f32_32x32x16_bf16 v[130:145], v[206:209], v[190:193], v[130:145]
	s_nop 10
	v_max_f32_e32 v1, v147, v147
	v_max_f32_e32 v194, v146, v146
	v_max_f32_e32 v1, v194, v1
	v_max3_f32 v1, v1, v148, v149
	v_max3_f32 v1, v1, v150, v151
	v_max3_f32 v1, v1, v152, v153
	v_max3_f32 v1, v1, v154, v155
	v_max3_f32 v1, v1, v156, v157
	v_max3_f32 v1, v1, v158, v159
	v_max3_f32 v1, v1, v160, v161
	v_max3_f32 v1, v1, v130, v131
	v_max3_f32 v1, v1, v132, v133
	v_max3_f32 v1, v1, v134, v135
	v_max3_f32 v1, v1, v136, v137
	v_max3_f32 v1, v1, v138, v139
	v_max3_f32 v1, v1, v140, v141
	v_max3_f32 v1, v1, v142, v143
	v_max3_f32 v1, v1, v144, v145
	v_mov_b32_e32 v194, v1
	s_nop 1
	v_permlane32_swap_b32_e32 v1, v194
	v_max_f32_e32 v194, v194, v194
	v_max_f32_e32 v1, v1, v1
	v_max_f32_e32 v1, v1, v194
	v_sub_f32_e32 v194, v1, v243
	v_cmp_ge_f32_e32 vcc, s8, v194
	v_max_f32_e32 v194, v243, v243
	v_max_f32_e32 v245, v194, v1
	v_sub_f32_e32 v1, v243, v245
	v_mul_f32_e32 v1, 0x3e0293ee, v1
	v_exp_f32_e32 v1, v1
	s_cmp_eq_u64 vcc, exec
	s_cselect_b64 s[8:9], -1, 0
	v_cndmask_b32_e64 v1, v1, 1.0, s[8:9]
	v_cmp_gt_f32_e32 vcc, 1.0, v1
	s_cbranch_vccz .LBB0_624
	s_and_saveexec_b64 s[54:55], s[6:7]
	ds_write_b32 v237, v1 offset:128
	s_or_b64 exec, exec, s[54:55]
	s_waitcnt lgkmcnt(0)
	v_add_u32_e32 v194, v211, v212
	ds_read_b128 v[206:209], v194 offset:224
	ds_read_b128 v[202:205], v194 offset:192
	ds_read_b128 v[198:201], v194 offset:160
	ds_read_b128 v[194:197], v194 offset:128
	s_waitcnt lgkmcnt(0)
	v_pk_mul_f32 v[126:127], v[126:127], v[206:207]
	v_pk_mul_f32 v[122:123], v[122:123], v[202:203]
	v_pk_mul_f32 v[118:119], v[118:119], v[198:199]
	v_pk_mul_f32 v[128:129], v[128:129], v[208:209]
	v_pk_mul_f32 v[124:125], v[124:125], v[204:205]
	v_pk_mul_f32 v[120:121], v[120:121], v[200:201]
	v_pk_mul_f32 v[116:117], v[116:117], v[196:197]
	v_pk_mul_f32 v[114:115], v[114:115], v[194:195]
	v_pk_mul_f32 v[110:111], v[110:111], v[206:207]
	v_pk_mul_f32 v[106:107], v[106:107], v[202:203]
	v_pk_mul_f32 v[102:103], v[102:103], v[198:199]
	v_pk_mul_f32 v[112:113], v[112:113], v[208:209]
	v_pk_mul_f32 v[108:109], v[108:109], v[204:205]
	v_pk_mul_f32 v[104:105], v[104:105], v[200:201]
	v_pk_mul_f32 v[100:101], v[100:101], v[196:197]
	v_pk_mul_f32 v[98:99], v[98:99], v[194:195]
	v_pk_mul_f32 v[94:95], v[94:95], v[206:207]
	v_pk_mul_f32 v[90:91], v[90:91], v[202:203]
	v_pk_mul_f32 v[86:87], v[86:87], v[198:199]
	v_pk_mul_f32 v[96:97], v[96:97], v[208:209]
	v_pk_mul_f32 v[92:93], v[92:93], v[204:205]
	v_pk_mul_f32 v[88:89], v[88:89], v[200:201]
	v_pk_mul_f32 v[84:85], v[84:85], v[196:197]
	v_pk_mul_f32 v[82:83], v[82:83], v[194:195]
	v_pk_mul_f32 v[78:79], v[78:79], v[206:207]
	v_pk_mul_f32 v[74:75], v[74:75], v[202:203]
	v_pk_mul_f32 v[70:71], v[70:71], v[198:199]
	v_pk_mul_f32 v[80:81], v[80:81], v[208:209]
	v_pk_mul_f32 v[76:77], v[76:77], v[204:205]
	v_pk_mul_f32 v[72:73], v[72:73], v[200:201]
	v_pk_mul_f32 v[68:69], v[68:69], v[196:197]
	v_pk_mul_f32 v[66:67], v[66:67], v[194:195]
	v_pk_mul_f32 v[62:63], v[62:63], v[206:207]
	v_pk_mul_f32 v[58:59], v[58:59], v[202:203]
	v_pk_mul_f32 v[54:55], v[54:55], v[198:199]
	v_pk_mul_f32 v[64:65], v[64:65], v[208:209]
	v_pk_mul_f32 v[60:61], v[60:61], v[204:205]
	v_pk_mul_f32 v[56:57], v[56:57], v[200:201]
	v_pk_mul_f32 v[52:53], v[52:53], v[196:197]
	v_pk_mul_f32 v[50:51], v[50:51], v[194:195]
	v_pk_mul_f32 v[46:47], v[46:47], v[206:207]
	v_pk_mul_f32 v[42:43], v[42:43], v[202:203]
	v_pk_mul_f32 v[38:39], v[38:39], v[198:199]
	v_pk_mul_f32 v[48:49], v[48:49], v[208:209]
	v_pk_mul_f32 v[44:45], v[44:45], v[204:205]
	v_pk_mul_f32 v[40:41], v[40:41], v[200:201]
	v_pk_mul_f32 v[36:37], v[36:37], v[196:197]
	v_pk_mul_f32 v[34:35], v[34:35], v[194:195]
	v_pk_mul_f32 v[30:31], v[30:31], v[206:207]
	v_pk_mul_f32 v[26:27], v[26:27], v[202:203]
	v_pk_mul_f32 v[22:23], v[22:23], v[198:199]
	v_pk_mul_f32 v[32:33], v[32:33], v[208:209]
	v_pk_mul_f32 v[28:29], v[28:29], v[204:205]
	v_pk_mul_f32 v[24:25], v[24:25], v[200:201]
	v_pk_mul_f32 v[20:21], v[20:21], v[196:197]
	v_pk_mul_f32 v[18:19], v[18:19], v[194:195]
	v_pk_mul_f32 v[14:15], v[14:15], v[206:207]
	v_pk_mul_f32 v[10:11], v[10:11], v[202:203]
	v_pk_mul_f32 v[6:7], v[6:7], v[198:199]
	v_pk_mul_f32 v[16:17], v[16:17], v[208:209]
	v_pk_mul_f32 v[12:13], v[12:13], v[204:205]
	v_pk_mul_f32 v[8:9], v[8:9], v[200:201]
	v_pk_mul_f32 v[4:5], v[4:5], v[196:197]
	v_pk_mul_f32 v[2:3], v[2:3], v[194:195]

; __global__ void __launch_bounds__(NTHREADS) mega(Params p_arg) {
	.amdhsa_kernel _Z4mega6Params
		.amdhsa_group_segment_fixed_size 16
		.amdhsa_private_segment_fixed_size 0
		.amdhsa_kernarg_size 528
		.amdhsa_user_sgpr_count 2
		.amdhsa_user_sgpr_dispatch_ptr 0
		.amdhsa_user_sgpr_queue_ptr 0
		.amdhsa_user_sgpr_kernarg_segment_ptr 1
		.amdhsa_user_sgpr_dispatch_id 0
		.amdhsa_user_sgpr_kernarg_preload_length 0
		.amdhsa_user_sgpr_kernarg_preload_offset 0
		.amdhsa_user_sgpr_private_segment_size 0
		.amdhsa_uses_dynamic_stack 0
		.amdhsa_enable_private_segment 0
		.amdhsa_system_sgpr_workgroup_id_x 1
		.amdhsa_system_sgpr_workgroup_id_y 0
		.amdhsa_system_sgpr_workgroup_id_z 0
		.amdhsa_system_sgpr_workgroup_info 0
		.amdhsa_system_vgpr_workitem_id 2
		.amdhsa_next_free_vgpr 256
		.amdhsa_next_free_sgpr 100
		.amdhsa_accum_offset 256
		.amdhsa_reserve_vcc 1
		.amdhsa_float_round_mode_32 0
		.amdhsa_float_round_mode_16_64 0
		.amdhsa_float_denorm_mode_32 3
		.amdhsa_float_denorm_mode_16_64 3
		.amdhsa_dx10_clamp 1
		.amdhsa_ieee_mode 1
		.amdhsa_fp16_overflow 0
		.amdhsa_tg_split 0
		.amdhsa_exception_fp_ieee_invalid_op 0
		.amdhsa_exception_fp_denorm_src 0
		.amdhsa_exception_fp_ieee_div_zero 0
		.amdhsa_exception_fp_ieee_overflow 0
		.amdhsa_exception_fp_ieee_underflow 0
		.amdhsa_exception_fp_ieee_inexact 0
		.amdhsa_exception_int_div_zero 0
	.end_amdhsa_kernel

; __global__ void __launch_bounds__(NTHREADS) mega(Params p_arg) {
amdhsa.kernels:
  - .agpr_count:     0
    .args:
      - .offset:         0
        .size:           272
        .value_kind:     by_value
      - .offset:         272
        .size:           4
        .value_kind:     hidden_block_count_x
      - .offset:         276
        .size:           4
        .value_kind:     hidden_block_count_y
      - .offset:         280
        .size:           4
        .value_kind:     hidden_block_count_z
      - .offset:         284
        .size:           2
        .value_kind:     hidden_group_size_x
      - .offset:         286
        .size:           2
        .value_kind:     hidden_group_size_y
      - .offset:         288
        .size:           2
        .value_kind:     hidden_group_size_z
      - .offset:         290
        .size:           2
        .value_kind:     hidden_remainder_x
      - .offset:         292
        .size:           2
        .value_kind:     hidden_remainder_y
      - .offset:         294
        .size:           2
        .value_kind:     hidden_remainder_z
      - .offset:         312
        .size:           8
        .value_kind:     hidden_global_offset_x
      - .offset:         320
        .size:           8
        .value_kind:     hidden_global_offset_y
      - .offset:         328
        .size:           8
        .value_kind:     hidden_global_offset_z
      - .offset:         336
        .size:           2
        .value_kind:     hidden_grid_dims
      - .offset:         360
        .size:           8
        .value_kind:     hidden_multigrid_sync_arg
      - .offset:         392
        .size:           4
        .value_kind:     hidden_dynamic_lds_size
    .group_segment_fixed_size: 16
    .kernarg_segment_align: 8
    .kernarg_segment_size: 528
    .language:       OpenCL C
    .language_version:
      - 2
      - 0
    .max_flat_workgroup_size: 512
    .name:           _Z4mega6Params
    .private_segment_fixed_size: 0
    .sgpr_count:     106
    .sgpr_spill_count: 23
    .symbol:         _Z4mega6Params.kd
    .uniform_work_group_size: 1
    .uses_dynamic_stack: false
    .vgpr_count:     256
    .vgpr_spill_count: 0
    .wavefront_size: 64
